# phase 0 item hand-out rebalanced between workgroups with 4 and with 3 long items
# speedup vs baseline: 1.0678x; 1.0001x over previous
; #define TIDX(p) ((p).wv * 64 + (int)__builtin_amdgcn_mbcnt_hi(~0u, __builtin_amdgcn_mbcnt_lo(~0u, 0u)))
; DI void phase0(const PX& p, unsigned char* smem) {
;   float* sm = (float*)smem;
;   if (blockIdx.x == 0 && TIDX(p) < 64) ((unsigned*)(p.ws + OFF_CNT))[TIDX(p)] = 0u;
;   const int n_mod = 384;
;   const int total = n_mod + MIX_TILES + N_FILT_ITEMS;
;   for (int it = blockIdx.x; it < total; it += gridDim.x) {
;     if (it < n_mod) { if (EN & 256) mod_partial(p, it, sm); }
;     else if (it < n_mod + N_FILT_ITEMS) { if (EN & 512) filter_item(p, it - n_mod, sm); }
;     else convert_mixer(p, 0, it - n_mod - N_FILT_ITEMS, sm);
;   }
; }
.LBB0_795:
	v_readlane_b32 s0, v253, 37
	v_readlane_b32 s1, v253, 38
	s_andn2_b64 vcc, exec, s[0:1]
	s_cbranch_vccnz .LBB0_1108
	v_readlane_b32 s1, v252, 0
	s_mov_b32 vcc_lo, 0
	v_writelane_b32 v255, vcc_lo, 63
	s_branch .LBB0_798
.LBB0_797:
	v_readlane_b32 vcc_lo, v255, 63
	s_add_i32 vcc_lo, vcc_lo, 1
	v_writelane_b32 v255, vcc_lo, 63
	v_readlane_b32 vcc_hi, v252, 0
	s_cmp_lt_u32 vcc_lo, 4
	s_cbranch_scc1 .Lp0_early
	s_sub_u32 vcc_lo, vcc_lo, 4
	s_cmp_lt_u32 vcc_hi, 0xa0
	s_cbranch_scc0 .Lp0_light
	s_cmp_ge_u32 vcc_lo, 22
	s_cbranch_scc1 .LBB0_1108
	s_mul_i32 s1, vcc_lo, 0xa0
	s_add_i32 s1, s1, vcc_hi
	s_addk_i32 s1, 0x400
	s_branch .Lp0_chk
.Lp0_light:
	s_cmp_ge_u32 vcc_lo, 52
	s_cbranch_scc1 .LBB0_1108
	s_mul_i32 s1, vcc_lo, 0x60
	s_add_i32 s1, s1, vcc_hi
	s_addk_i32 s1, 0x1120
	s_branch .Lp0_chk
.Lp0_early:
	s_lshl_b32 s1, vcc_lo, 8
	s_add_i32 s1, s1, vcc_hi
.Lp0_chk:
	s_cmpk_gt_i32 s1, 0x24cf
	s_cbranch_scc1 .LBB0_1108
